# P12 row loop: the one hoisted next-row register copy and its vmcnt(3) wait moved to the loop end, so the row's reduction overlaps the load latency
# speedup vs baseline: 1.0020x; 1.0020x over previous
.LBB0_1448:
	s_waitcnt vmcnt(15)
	v_lshlrev_b32_e32 v94, 16, v82
	v_and_b32_e32 v95, 0xffff0000, v82
	v_lshlrev_b32_e32 v82, 16, v83
	v_and_b32_e32 v83, 0xffff0000, v83
	s_waitcnt vmcnt(11)
	v_lshlrev_b32_e32 v96, 16, v84
	v_and_b32_e32 v97, 0xffff0000, v84
	v_lshlrev_b32_e32 v84, 16, v85
	v_and_b32_e32 v85, 0xffff0000, v85
	v_pk_fma_f32 v[94:95], v[38:39], v[96:97], v[94:95]
	v_pk_fma_f32 v[82:83], v[36:37], v[84:85], v[82:83]
	v_pk_mul_f32 v[96:97], v[94:95], v[94:95]
	v_pk_mul_f32 v[84:85], v[82:83], v[82:83]
	v_lshlrev_b32_e32 v102, 16, v70
	v_pk_mov_b32 v[98:99], v[96:97], v[84:85] op_sel:[1,0]
	v_mov_b32_e32 v97, v85
	v_pk_add_f32 v[84:85], v[98:99], v[96:97]
	v_lshlrev_b32_e32 v96, 16, v78
	v_and_b32_e32 v97, 0xffff0000, v78
	v_lshlrev_b32_e32 v78, 16, v79
	v_and_b32_e32 v79, 0xffff0000, v79
	s_waitcnt vmcnt(10)
	v_lshlrev_b32_e32 v98, 16, v80
	v_and_b32_e32 v99, 0xffff0000, v80
	v_lshlrev_b32_e32 v80, 16, v81
	v_and_b32_e32 v81, 0xffff0000, v81
	v_pk_fma_f32 v[96:97], v[42:43], v[98:99], v[96:97]
	v_pk_fma_f32 v[78:79], v[40:41], v[80:81], v[78:79]
	v_pk_mul_f32 v[98:99], v[96:97], v[96:97]
	v_pk_mul_f32 v[80:81], v[78:79], v[78:79]
	v_and_b32_e32 v103, 0xffff0000, v70
	v_pk_mov_b32 v[100:101], v[98:99], v[80:81] op_sel:[1,0]
	v_mov_b32_e32 v99, v81
	v_pk_add_f32 v[80:81], v[100:101], v[98:99]
	v_lshlrev_b32_e32 v98, 16, v74
	v_and_b32_e32 v99, 0xffff0000, v74
	v_lshlrev_b32_e32 v74, 16, v75
	v_and_b32_e32 v75, 0xffff0000, v75
	s_waitcnt vmcnt(9)
	v_lshlrev_b32_e32 v100, 16, v76
	v_and_b32_e32 v101, 0xffff0000, v76
	v_lshlrev_b32_e32 v76, 16, v77
	v_and_b32_e32 v77, 0xffff0000, v77
	v_pk_add_f32 v[80:81], v[80:81], v[80:81] op_sel_hi:[0,1]
	v_pk_fma_f32 v[74:75], v[44:45], v[76:77], v[74:75]
	v_pk_fma_f32 v[76:77], v[46:47], v[100:101], v[98:99]
	v_lshlrev_b32_e32 v70, 16, v71
	v_mul_f32_e32 v80, v76, v76
	v_pk_fma_f32 v[98:99], v[76:77], v[76:77], v[80:81] op_sel_hi:[1,1,0]
	v_mul_f32_e32 v80, v74, v74
	v_and_b32_e32 v71, 0xffff0000, v71
	s_waitcnt vmcnt(8)
	v_lshlrev_b32_e32 v104, 16, v72
	v_and_b32_e32 v105, 0xffff0000, v72
	v_lshlrev_b32_e32 v72, 16, v73
	v_and_b32_e32 v73, 0xffff0000, v73
	v_pk_add_f32 v[84:85], v[84:85], v[84:85] op_sel_hi:[0,1]
	v_pk_fma_f32 v[100:101], v[74:75], v[74:75], v[80:81] op_sel_hi:[1,1,0]
	v_pk_fma_f32 v[106:107], v[48:49], v[72:73], v[70:71]
	v_pk_fma_f32 v[102:103], v[50:51], v[104:105], v[102:103]
	v_mul_f32_e32 v84, v106, v106
	v_mul_f32_e32 v98, v102, v102
	v_mul_f32_e32 v100, v103, v103
	v_mul_f32_e32 v80, v107, v107
	v_pk_add_f32 v[70:71], v[98:99], v[100:101]
	v_pk_add_f32 v[72:73], v[84:85], v[80:81]
	s_add_i32 s2, s2, 1
	v_pk_add_f32 v[70:71], v[70:71], v[72:73]
	v_mov_b32_e32 v84, v30
	v_add_f32_e32 v70, v70, v71
	ds_bpermute_b32 v71, v86, v70
	v_mov_b32_e32 v85, v31
	s_cmp_lt_i32 s2, s6
	s_waitcnt lgkmcnt(0)
	v_add_f32_e32 v70, v70, v71
	ds_bpermute_b32 v71, v87, v70
	s_waitcnt lgkmcnt(0)
	v_add_f32_e32 v70, v70, v71
	ds_bpermute_b32 v71, v88, v70
	s_waitcnt lgkmcnt(0)
	v_add_f32_e32 v70, v70, v71
	ds_bpermute_b32 v71, v89, v70
	s_waitcnt lgkmcnt(0)
	v_add_f32_e32 v70, v70, v71
	ds_bpermute_b32 v71, v90, v70
	s_waitcnt lgkmcnt(0)
	v_add_f32_e32 v70, v70, v71
	ds_bpermute_b32 v71, v91, v70
	s_waitcnt lgkmcnt(0)
	v_add_f32_e32 v70, v70, v71
	v_fmamk_f32 v70, v70, 0x3a800000, v92
	v_mul_f32_e32 v71, 0x4f800000, v70
	v_cmp_gt_f32_e32 vcc, s3, v70
	s_nop 1
	v_cndmask_b32_e32 v70, v70, v71, vcc
	v_sqrt_f32_e32 v71, v70
	s_nop 0
	v_add_u32_e32 v72, -1, v71
	v_fma_f32 v73, -v72, v71, v70
	v_cmp_ge_f32_e64 s[0:1], 0, v73
	v_add_u32_e32 v73, 1, v71
	s_nop 0
	v_cndmask_b32_e64 v72, v71, v72, s[0:1]
	v_fma_f32 v71, -v73, v71, v70
	v_cmp_lt_f32_e64 s[0:1], 0, v71
	s_nop 1
	v_cndmask_b32_e64 v71, v72, v73, s[0:1]
	v_mul_f32_e32 v72, 0x37800000, v71
	v_cndmask_b32_e32 v71, v71, v72, vcc
	v_cmp_class_f32_e32 vcc, v70, v93
	s_nop 1
	v_cndmask_b32_e32 v70, v71, v70, vcc
	v_div_scale_f32 v71, s[0:1], v70, v70, 1.0
	v_rcp_f32_e32 v72, v71
	s_nop 0
	v_fma_f32 v73, -v71, v72, 1.0
	v_fmac_f32_e32 v72, v73, v72
	v_div_scale_f32 v73, vcc, 1.0, v70, 1.0
	v_mul_f32_e32 v80, v73, v72
	v_fma_f32 v81, -v71, v80, v73
	v_fmac_f32_e32 v80, v81, v72
	v_fma_f32 v71, -v71, v80, v73
	v_div_fmas_f32 v71, v71, v72, v80
	v_div_fixup_f32 v80, v71, v70, 1.0
	v_pk_mul_f32 v[70:71], v[94:95], v[80:81] op_sel_hi:[1,0]
	v_pk_mul_f32 v[72:73], v[82:83], v[80:81] op_sel_hi:[1,0]
	v_pk_mul_f32 v[70:71], v[0:1], v[70:71]
	v_pk_mul_f32 v[72:73], v[2:3], v[72:73]
	global_store_dwordx4 v[52:53], v[70:73], off nt
	v_mov_b32_e32 v82, v22
	v_mov_b32_e32 v83, v23
	v_pk_mul_f32 v[70:71], v[96:97], v[80:81] op_sel_hi:[1,0]
	v_pk_mul_f32 v[72:73], v[78:79], v[80:81] op_sel_hi:[1,0]
	v_pk_mul_f32 v[70:71], v[4:5], v[70:71]
	v_pk_mul_f32 v[72:73], v[6:7], v[72:73]
	global_store_dwordx4 v[52:53], v[70:73], off offset:1024 nt
	v_mov_b32_e32 v78, v20
	v_mov_b32_e32 v79, v21
	v_pk_mul_f32 v[70:71], v[76:77], v[80:81] op_sel_hi:[1,0]
	v_pk_mul_f32 v[72:73], v[74:75], v[80:81] op_sel_hi:[1,0]
	v_pk_mul_f32 v[70:71], v[8:9], v[70:71]
	v_pk_mul_f32 v[72:73], v[10:11], v[72:73]
	global_store_dwordx4 v[52:53], v[70:73], off offset:2048 nt
	v_mov_b32_e32 v74, v18
	v_mov_b32_e32 v75, v19
	v_pk_mul_f32 v[70:71], v[102:103], v[80:81] op_sel_hi:[1,0]
	v_pk_mul_f32 v[72:73], v[106:107], v[80:81] op_sel_hi:[1,0]
	v_pk_mul_f32 v[70:71], v[12:13], v[70:71]
	v_pk_mul_f32 v[72:73], v[14:15], v[72:73]
	global_store_dwordx4 v[52:53], v[70:73], off offset:3072 nt
	s_waitcnt vmcnt(6)
	v_mov_b32_e32 v80, v28
	v_mov_b32_e32 v81, v29
	v_mov_b32_e32 v70, v16
	v_mov_b32_e32 v71, v17
	s_waitcnt vmcnt(5)
	v_mov_b32_e32 v76, v26
	v_mov_b32_e32 v77, v27
	s_waitcnt vmcnt(4)
	v_mov_b32_e32 v72, v24
	v_mov_b32_e32 v73, v25
	v_lshl_add_u64 v[52:53], v[52:53], 0, s[4:5]
	v_mov_b64_e32 v[30:31], v[68:69]
	v_mov_b64_e32 v[16:17], v[60:61]
	v_mov_b64_e32 v[18:19], v[58:59]
	v_mov_b64_e32 v[20:21], v[56:57]
	v_mov_b64_e32 v[22:23], v[54:55]
	v_mov_b64_e32 v[24:25], v[62:63]
	v_mov_b64_e32 v[26:27], v[64:65]
	v_mov_b64_e32 v[28:29], v[66:67]
	s_cbranch_scc0 .LBB0_1451
